# P4 LayerNorm stats exchange via self-tagged slots (sign bit of M2, slots zeroed in prologue): no counter atomic, ack wait, acquire or extra barrier; plus P0 x-loop rewrite
# speedup vs baseline: 1.0048x; 1.0048x over previous
.LBB0_55:
	v_lshlrev_b32_e32 v2, 3, v130
	s_lshl_b32 s0, s66, 12
	v_add_u32_e32 v2, s0, v2
	v_add_u32_e32 v2, 0x180000, v2
	v_mov_b32_e32 v4, 0
	v_mov_b32_e32 v5, 0
	global_store_dwordx2 v2, v[4:5], s[64:65] sc0 sc1
	v_writelane_b32 v254, s64, 11
	s_ashr_i32 s67, s66, 31
	v_ashrrev_i32_e32 v131, 31, v130
	v_writelane_b32 v254, s65, 12
	v_writelane_b32 v254, s66, 13
	s_lshl_b64 s[0:1], s[66:67], 9
	s_ashr_i32 s3, s2, 31
	v_writelane_b32 v254, s67, 14
	v_writelane_b32 v254, s0, 15
	s_lshl_b64 s[46:47], s[2:3], 9
	s_nop 0
	v_writelane_b32 v254, s1, 16
	v_lshl_add_u64 v[2:3], s[0:1], 0, v[130:131]
	s_mov_b64 s[0:1], 0x10000
	v_cmp_gt_u64_e32 vcc, s[0:1], v[2:3]
	s_and_saveexec_b64 s[4:5], vcc
	s_cbranch_execz .LBB0_102
	v_readlane_b32 s0, v254, 13
	v_readlane_b32 s1, v254, 14
	s_lshl_b64 s[0:1], s[0:1], 11
	v_readlane_b32 s6, v254, 11
	v_readlane_b32 s7, v254, 12
	s_add_u32 s0, s6, s0
	s_addc_u32 s1, s7, s1
	v_lshl_add_u64 v[4:5], v[130:131], 2, s[0:1]
	s_mov_b64 s[0:1], 0x100000
	v_lshl_add_u64 v[4:5], v[4:5], 0, s[0:1]
	s_mov_b32 s10, 0x6dc9c883
	s_mov_b32 s14, 0x54442d18
	s_mov_b32 s18, 0x33145c07
	s_mov_b32 s48, 0x55555555
	s_mov_b32 s54, 0x9999999a
	s_mov_b32 s56, 0x11111111
	s_mov_b32 s58, 0x18618618
	s_mov_b32 s60, 0x92492492
	s_mov_b32 s62, 0x1c71c71c
	s_mov_b32 s64, 0x16c16c17
	s_mov_b32 s66, 0x29e4129e
	s_mov_b32 s68, 0xf07c1f08
	s_mov_b32 s70, 0x1a41a41a
	s_mov_b32 s72, 0x16816817
	s_mov_b32 s74, 0x13813814
	s_mov_b32 s78, 0x1e1e1e1e
	s_mov_b32 s80, 0x1ac5701b
	s_mov_b32 s82, 0xfd017f40
	s_mov_b32 s84, 0x308158ed
	s_mov_b32 s88, 0x4046ed29
	s_mov_b32 s90, 0xb51f5e1a
	s_mov_b32 s92, 0x76b981db
	s_mov_b32 s94, 0xb4e81b4f
	s_mov_b32 s96, 0x7f9b2ce6
	s_mov_b32 s40, 0xc201756d
	s_mov_b32 s50, 0x6b015ac0
	s_mov_b32 s20, 0x25d51f87
	s_mov_b32 s0, 0x19e0119e
	s_mov_b32 s36, 0x12d50a0
	v_and_b32_e32 v1, 15, v130
	s_lshl_b64 s[6:7], s[2:3], 11
	s_mov_b64 s[8:9], 0
	s_mov_b32 s11, 0x3fc45f30
	s_mov_b32 s15, 0xc01921fb
	s_mov_b32 s19, 0xbcb1a626
	s_mov_b32 s49, 0x3fc55555
	s_mov_b32 s53, 0x3fb55555
	s_mov_b32 s55, 0x3fa99999
	s_mov_b32 s57, 0x3fa11111
	s_mov_b32 s59, 0x3f986186
	s_mov_b32 s61, 0x3f924924
	s_mov_b32 s63, 0x3f8c71c7
	s_mov_b32 s65, 0x3f86c16c
	s_mov_b32 s67, 0x3f829e41
	s_mov_b32 s69, 0x3f7f07c1
	s_mov_b32 s71, 0x3f7a41a4
	s_mov_b32 s73, 0x3f768168
	s_mov_b32 s75, 0x3f738138
	s_mov_b32 s77, 0x3f711111
	s_mov_b32 s79, 0x3f6e1e1e
	s_mov_b32 s81, 0x3f6ac570
	s_mov_b32 s83, 0x3f67f405
	s_mov_b32 s85, 0x3f658ed2
	s_mov_b32 s87, 0x3f638138
	s_mov_b32 s89, 0x3f61bb4a
	s_mov_b32 s91, 0x3f603091
	s_mov_b32 s93, 0x3f5dae60
	s_mov_b32 s95, 0x3f5b4e81
	s_mov_b32 s97, 0x3f5934c6
	s_mov_b32 s41, 0x3f5756ca
	s_mov_b32 s51, 0x3f55ac05
	s_mov_b32 s21, 0x3f542d66
	s_mov_b32 s1, 0xbf519e01
	s_mov_b32 s37, 0xbf52d50a
	v_mov_b32_e32 v6, 0xe0306bb5
	v_mov_b32_e32 v7, 0x3ed30c94
	v_mov_b32_e32 v8, 0xe49b7c16
	v_mov_b32_e32 v9, 0x3ee5a0f4
	v_mov_b32_e32 v10, 0x12e39eda
	v_mov_b32_e32 v11, 0x3ef88ec2
	v_mov_b32_e32 v12, 0x8e4aa32f
	v_mov_b32_e32 v13, 0x3f0be218
	v_mov_b32_e32 v14, 0x4a44fa06
	v_mov_b32_e32 v15, 0x3f1fa8b8
	v_mov_b32_e32 v16, 0xf20d667d
	v_mov_b32_e32 v17, 0x3f31f91e
	v_mov_b32_e32 v18, 0x97ad3991
	v_mov_b32_e32 v19, 0x3f446831
	v_mov_b32_e32 v20, 0x3fff3717
	v_mov_b32_e32 v21, 0x3f572ba4
	v_mov_b32_e32 v22, 0xf0a6907b
	v_mov_b32_e32 v23, 0x3f6a4ee3
	v_mov_b32_e32 v24, 0xc8c0acee
	v_mov_b32_e32 v25, 0x3f7ddee9
	v_mov_b32_e32 v26, 0x52389081
	v_mov_b32_e32 v27, 0x3f90f538
	v_mov_b32_e32 v28, 0x1f5fa45
	v_mov_b32_e32 v29, 0x3fa34119
	v_mov_b32_e32 v30, 0x98e68d6e
	v_mov_b32_e32 v31, 0x3fb5dc95
	v_mov_b32_e32 v32, 0xe352b568
	v_mov_b32_e32 v33, 0x3fc8d275
	v_mov_b32_e32 v34, 0x672e7587
	v_mov_b32_e32 v35, 0x3fdc2ef7
	s_branch .LBB0_61

.LBB0_516:
	s_or_b64 exec, exec, s[8:9]
	s_waitcnt lgkmcnt(0)
	s_barrier
	v_add_u32_e32 v128, s48, v198
	s_waitcnt lgkmcnt(0)
	v_ashrrev_i32_e32 v129, 31, v128
	s_and_saveexec_b64 s[8:9], s[4:5]
	s_cbranch_execz .LBB0_518
	ds_read_b128 v[130:133], v217
	ds_read_b128 v[134:137], v217 offset:16
	s_waitcnt lgkmcnt(1)
	v_add_f32_e32 v138, v130, v132
	s_waitcnt lgkmcnt(0)
	v_add_f32_e32 v138, v138, v134
	v_add_f32_e32 v139, v138, v136
	v_fmamk_f32 v130, v139, 0xbe800000, v130
	v_fmac_f32_e32 v132, 0xbe800000, v139
	v_fmamk_f32 v134, v139, 0xbe800000, v134
	v_fmac_f32_e32 v136, 0xbe800000, v139
	v_mul_f32_e32 v141, v130, v130
	v_mul_f32_e32 v143, v132, v132
	v_mul_f32_e32 v145, v134, v134
	v_mul_f32_e32 v147, v136, v136
	v_mov_b32_e32 v140, v131
	v_mov_b32_e32 v142, v133
	v_mov_b32_e32 v144, v135
	v_mov_b32_e32 v146, v137
	v_pk_add_f32 v[130:131], v[140:141], v[142:143]
	v_pk_add_f32 v[132:133], v[144:145], v[146:147]
	v_mul_f32_e32 v138, 0x3e800000, v139
	v_pk_add_f32 v[130:131], v[130:131], v[132:133]
	v_lshlrev_b64 v[132:133], 6, v[128:129]
	v_fmac_f32_e32 v130, 0x42800000, v131
	v_lshl_add_u64 v[132:133], s[16:17], 0, v[132:133]
	v_or_b32_e32 v139, 0x80000000, v130
	global_store_dwordx2 v[132:133], v[138:139], off sc1
.LBB0_518:
	s_or_b64 exec, exec, s[8:9]
	s_and_saveexec_b64 s[46:47], s[4:5]
	s_cbranch_execz .LBB0_529
	v_lshlrev_b64 v[128:129], 6, v[128:129]
	v_lshl_add_u64 v[128:129], s[22:23], 0, v[128:129]
	s_mov_b32 s8, 0
	s_mov_b64 s[50:51], exec
	s_mov_b64 exec, 1
.Llnx_pre:
	global_load_dwordx4 v[130:133], v[128:129], off sc1
	global_load_dwordx4 v[134:137], v[128:129], off offset:16 sc1
	global_load_dwordx4 v[138:141], v[128:129], off offset:32 sc1
	global_load_dwordx4 v[142:145], v[128:129], off offset:48 sc1
	s_waitcnt vmcnt(0)
	v_and_b32_e32 v148, v131, v133
	v_and_b32_e32 v149, v135, v137
	v_and_b32_e32 v150, v139, v141
	v_and_b32_e32 v151, v143, v145
	v_and_b32_e32 v148, v148, v149
	v_and_b32_e32 v150, v150, v151
	v_and_b32_e32 v148, v148, v150
	v_cmp_gt_i32_e32 vcc, 0, v148
	s_cbranch_vccnz .Llnx_pre_done
	s_add_i32 s8, s8, 1
	s_cmp_lt_u32 s8, 0x40000
	s_cbranch_scc0 .Llnx_pre_done
	s_sleep 4
	s_branch .Llnx_pre
.Llnx_pre_done:
	s_mov_b64 exec, s[50:51]
.Llnx_poll:
	global_load_dwordx2 v[130:131], v[128:129], off sc1
	global_load_dwordx2 v[132:133], v[128:129], off offset:8 sc1
	global_load_dwordx2 v[134:135], v[128:129], off offset:16 sc1
	global_load_dwordx2 v[136:137], v[128:129], off offset:24 sc1
	global_load_dwordx2 v[138:139], v[128:129], off offset:32 sc1
	global_load_dwordx2 v[140:141], v[128:129], off offset:40 sc1
	global_load_dwordx2 v[142:143], v[128:129], off offset:48 sc1
	global_load_dwordx2 v[146:147], v[128:129], off offset:56 sc1
	s_waitcnt vmcnt(0)
	v_and_b32_e32 v148, v131, v133
	v_and_b32_e32 v149, v135, v137
	v_and_b32_e32 v150, v139, v141
	v_and_b32_e32 v151, v143, v147
	v_and_b32_e32 v148, v148, v149
	v_and_b32_e32 v150, v150, v151
	v_and_b32_e32 v148, v148, v150
	v_cmp_gt_i32_e32 vcc, 0, v148
	s_andn2_b64 s[50:51], exec, vcc
	s_cbranch_scc0 .Llnx_ready
	s_add_i32 s8, s8, 1
	s_cmp_lt_u32 s8, 0x100000
	s_cbranch_scc0 .Llnx_ready
	s_sleep 1
	s_branch .Llnx_poll
.Llnx_ready:
	v_and_b32_e32 v131, 0x7fffffff, v131
	v_and_b32_e32 v133, 0x7fffffff, v133
	v_and_b32_e32 v135, 0x7fffffff, v135
	v_and_b32_e32 v137, 0x7fffffff, v137
	v_and_b32_e32 v139, 0x7fffffff, v139
	v_and_b32_e32 v141, 0x7fffffff, v141
	v_and_b32_e32 v143, 0x7fffffff, v143
	v_mov_b32_e32 v128, v146
	v_and_b32_e32 v129, 0x7fffffff, v147
	s_waitcnt vmcnt(7)
	v_add_f32_e32 v144, 0, v130
	s_waitcnt vmcnt(6)
	v_add_f32_e32 v144, v144, v132
	s_waitcnt vmcnt(5)
	v_add_f32_e32 v144, v144, v134
	s_waitcnt vmcnt(4)
	v_add_f32_e32 v144, v144, v136
	s_waitcnt vmcnt(3)
	v_add_f32_e32 v144, v144, v138
	s_waitcnt vmcnt(2)
	v_add_f32_e32 v144, v144, v140
	s_waitcnt vmcnt(1)
	v_add_f32_e32 v144, v144, v142
	s_waitcnt vmcnt(0)
	v_add_f32_e32 v144, v144, v128
	v_fmamk_f32 v130, v144, 0xbe000000, v130
	v_fmamk_f32 v132, v144, 0xbe000000, v132
	v_fmamk_f32 v128, v144, 0xbe000000, v128
	v_mul_f32_e32 v145, 0x43800000, v130
	v_fmamk_f32 v134, v144, 0xbe000000, v134
	v_mul_f32_e32 v146, 0x43800000, v132
	v_mul_f32_e32 v152, 0x43800000, v128
	v_fmac_f32_e32 v131, v130, v145
	v_fmamk_f32 v136, v144, 0xbe000000, v136
	v_mul_f32_e32 v147, 0x43800000, v134
	v_fmac_f32_e32 v133, v132, v146
	v_fmac_f32_e32 v129, v128, v152
	v_add_f32_e32 v128, 0, v131
	v_fmamk_f32 v138, v144, 0xbe000000, v138
	v_mul_f32_e32 v148, 0x43800000, v136
	v_fmac_f32_e32 v135, v134, v147
	v_add_f32_e32 v128, v133, v128
	v_fmamk_f32 v140, v144, 0xbe000000, v140
	v_mul_f32_e32 v149, 0x43800000, v138
	v_fmac_f32_e32 v137, v136, v148
	v_add_f32_e32 v128, v135, v128
	v_fmamk_f32 v142, v144, 0xbe000000, v142
	v_mul_f32_e32 v150, 0x43800000, v140
	v_fmac_f32_e32 v139, v138, v149
	v_add_f32_e32 v128, v137, v128
	v_mul_f32_e32 v151, 0x43800000, v142
	v_fmac_f32_e32 v141, v140, v150
	v_add_f32_e32 v128, v139, v128
	v_fmac_f32_e32 v143, v142, v151
	v_add_f32_e32 v128, v141, v128
	v_add_f32_e32 v128, v143, v128
	v_add_f32_e32 v128, v129, v128
	v_fmamk_f32 v128, v128, 0x3a000000, v218
	v_mul_f32_e32 v129, 0x4f800000, v128
	v_cmp_gt_f32_e32 vcc, s60, v128
	s_nop 1
	v_cndmask_b32_e32 v128, v128, v129, vcc
	v_sqrt_f32_e32 v129, v128
	s_nop 0
	v_add_u32_e32 v130, -1, v129
	v_add_u32_e32 v131, 1, v129
	v_fma_f32 v132, -v130, v129, v128
	v_fma_f32 v133, -v131, v129, v128
	v_cmp_ge_f32_e64 s[8:9], 0, v132
	s_nop 1
	v_cndmask_b32_e64 v129, v129, v130, s[8:9]
	v_cmp_lt_f32_e64 s[8:9], 0, v133
	s_nop 1
	v_cndmask_b32_e64 v129, v129, v131, s[8:9]
	v_mul_f32_e32 v130, 0x37800000, v129
	v_cndmask_b32_e32 v129, v129, v130, vcc
	v_cmp_class_f32_e32 vcc, v128, v219
	s_nop 1
	v_cndmask_b32_e32 v129, v129, v128, vcc
	v_div_scale_f32 v130, s[8:9], v129, v129, 1.0
	v_rcp_f32_e32 v131, v130
	v_div_scale_f32 v132, vcc, 1.0, v129, 1.0
	v_mul_f32_e32 v128, 0x3e000000, v144
	v_fma_f32 v133, -v130, v131, 1.0
	v_fmac_f32_e32 v131, v133, v131
	v_mul_f32_e32 v133, v132, v131
	v_fma_f32 v134, -v130, v133, v132
	v_fmac_f32_e32 v133, v134, v131
	v_fma_f32 v130, -v130, v133, v132
	v_div_fmas_f32 v130, v130, v131, v133
	v_div_fixup_f32 v129, v130, v129, 1.0
	ds_write_b64 v199, v[128:129]
